# DSA: no workgroup barrier between the top-k select and the attention step (each wave's K/V ring overlays only its own two queries' score rows)
# speedup vs baseline: 1.0036x; 1.0036x over previous
.LBB0_470:
	s_waitcnt lgkmcnt(0)
	v_readlane_b32 s20, v254, 30
	v_readlane_b32 s21, v254, 31
	v_readlane_b32 s22, v253, 1
	v_readlane_b32 s2, v254, 17
	v_readlane_b32 s3, v254, 18
	v_readlane_b32 s4, v254, 23
	v_readlane_b32 s5, v254, 24
	v_readlane_b32 s6, v254, 15
	v_readlane_b32 s7, v254, 16
	s_lshl_b32 s23, s20, 19
	s_add_u32 s2, s2, s23
	s_addc_u32 s3, s3, 0
	s_add_u32 s4, s4, s23
	s_addc_u32 s5, s5, 0
	s_lshl_b32 s8, s22, 14
	s_lshl_b32 s12, s22, 1
	s_add_i32 s12, s12, s21
	s_lshl_b32 s14, s22, 10
	s_min_i32 s9, s61, 0x100
	s_lshr_b32 s10, s9, 6
	s_mov_b32 s11, 0
	v_and_b32_e32 v165, 15, v221
	v_bfe_u32 v166, v221, 4, 2
	v_lshlrev_b32_e32 v167, 2, v166
	v_xor_b32_e32 v167, v165, v167
	v_lshlrev_b32_e32 v10, 4, v167
	v_xor_b32_e32 v168, 1, v167
	v_lshlrev_b32_e32 v11, 4, v168
	v_xor_b32_e32 v168, 2, v167
	v_lshlrev_b32_e32 v12, 4, v168
	v_xor_b32_e32 v168, 3, v167
	v_lshlrev_b32_e32 v13, 4, v168
	v_lshlrev_b32_e32 v156, 1, v166
	v_add_u32_e32 v156, 0x20000, v156
	v_and_b32_e32 v167, 7, v165
	v_lshlrev_b32_e32 v167, 8, v167
	v_lshl_add_u32 v157, v166, 4, v167
	v_and_b32_e32 v167, 3, v165
	v_lshlrev_b32_e32 v167, 2, v167
	v_bfe_u32 v168, v165, 2, 2
	v_or_b32_e32 v167, v167, v168
	v_lshlrev_b32_e32 v170, 8, v165
	v_add_u32_e32 v170, s8, v170
	v_mov_b32_e32 v168, v166
	v_xor_b32_e32 v168, v168, v167
	v_lshl_add_u32 v18, v168, 4, v170
	v_or_b32_e32 v168, 4, v166
	v_xor_b32_e32 v168, v168, v167
	v_lshl_add_u32 v19, v168, 4, v170
	v_or_b32_e32 v168, 8, v166
	v_xor_b32_e32 v168, v168, v167
	v_lshl_add_u32 v20, v168, 4, v170
	v_or_b32_e32 v168, 12, v166
	v_xor_b32_e32 v168, v168, v167
	v_lshl_add_u32 v21, v168, 4, v170
	v_lshrrev_b32_e32 v170, 2, v165
	v_and_b32_e32 v171, 3, v165
	v_lshl_add_u32 v172, v166, 2, v170
	v_lshl_add_u32 v173, v170, 2, v166
	v_lshlrev_b32_e32 v172, 8, v172
	v_and_b32_e32 v167, 1, v171
	v_lshl_add_u32 v172, v167, 3, v172
	v_add_u32_e32 v172, s8, v172
	v_lshrrev_b32_e32 v167, 1, v171
	v_xor_b32_e32 v168, v167, v173
	v_lshl_add_u32 v148, v168, 4, v172
	v_or_b32_e32 v168, 2, v167
	v_xor_b32_e32 v168, v168, v173
	v_lshl_add_u32 v149, v168, 4, v172
	v_or_b32_e32 v168, 4, v167
	v_xor_b32_e32 v168, v168, v173
	v_lshl_add_u32 v150, v168, 4, v172
	v_or_b32_e32 v168, 6, v167
	v_xor_b32_e32 v168, v168, v173
	v_lshl_add_u32 v151, v168, 4, v172
	v_or_b32_e32 v168, 8, v167
	v_xor_b32_e32 v168, v168, v173
	v_lshl_add_u32 v152, v168, 4, v172
	v_or_b32_e32 v168, 10, v167
	v_xor_b32_e32 v168, v168, v173
	v_lshl_add_u32 v153, v168, 4, v172
	v_or_b32_e32 v168, 12, v167
	v_xor_b32_e32 v168, v168, v173
	v_lshl_add_u32 v154, v168, 4, v172
	v_or_b32_e32 v168, 14, v167
	v_xor_b32_e32 v168, v168, v173
	v_lshl_add_u32 v155, v168, 4, v172
	v_lshlrev_b32_e32 v158, 10, v166
	v_lshl_add_u32 v158, v165, 1, v158
	v_add_u32_e32 v158, s8, v158
	v_add_u32_e32 v158, 0x2000, v158
	v_lshlrev_b32_e32 v160, 4, v221
	v_add_u32_e32 v159, s8, v160
	v_add_u32_e32 v159, 0x2000, v159
	s_lshl_b32 s13, s12, 12
	v_add_u32_e32 v162, s13, v157
	global_load_dwordx4 v[88:91], v162, s[6:7] offset:0
	global_load_dwordx4 v[92:95], v162, s[6:7] offset:64
	global_load_dwordx4 v[96:99], v162, s[6:7] offset:128
	global_load_dwordx4 v[100:103], v162, s[6:7] offset:192
	s_mov_b32 s18, s14
	s_mov_b64 s[16:17], s[2:3]
	v_add_u32_e32 v161, s18, v156
	ds_read_u16 v0, v161 offset:0
	ds_read_u16 v1, v161 offset:8
	ds_read_u16 v2, v161 offset:16
	ds_read_u16 v3, v161 offset:24
	ds_read_u16 v4, v161 offset:32
	ds_read_u16 v5, v161 offset:40
	ds_read_u16 v6, v161 offset:48
	ds_read_u16 v7, v161 offset:56
	s_waitcnt lgkmcnt(7)
	s_add_i32 m0, s8, 0x0
	v_lshl_add_u32 v8, v0, 8, v10
	global_load_lds_dwordx4 v8, s[16:17]
	s_waitcnt lgkmcnt(6)
	s_add_i32 m0, s8, 0x400
	v_lshl_add_u32 v9, v1, 8, v11
	global_load_lds_dwordx4 v9, s[16:17]
	s_waitcnt lgkmcnt(5)
	s_add_i32 m0, s8, 0x800
	v_lshl_add_u32 v8, v2, 8, v12
	global_load_lds_dwordx4 v8, s[16:17]
	s_waitcnt lgkmcnt(4)
	s_add_i32 m0, s8, 0xc00
	v_lshl_add_u32 v9, v3, 8, v13
	global_load_lds_dwordx4 v9, s[16:17]
	s_waitcnt lgkmcnt(3)
	s_add_i32 m0, s8, 0x1000
	v_lshl_add_u32 v8, v4, 8, v10
	global_load_lds_dwordx4 v8, s[16:17]
	s_waitcnt lgkmcnt(2)
	s_add_i32 m0, s8, 0x1400
	v_lshl_add_u32 v9, v5, 8, v11
	global_load_lds_dwordx4 v9, s[16:17]
	s_waitcnt lgkmcnt(1)
	s_add_i32 m0, s8, 0x1800
	v_lshl_add_u32 v8, v6, 8, v12
	global_load_lds_dwordx4 v8, s[16:17]
	s_waitcnt lgkmcnt(0)
	s_add_i32 m0, s8, 0x1c00
	v_lshl_add_u32 v9, v7, 8, v13
	global_load_lds_dwordx4 v9, s[16:17]
	s_cmp_eq_u32 s10, 1
	s_cbranch_scc1 .Lattn_q2
	s_cmp_eq_u32 s10, 2
	s_cbranch_scc1 .Lattn_q4
	s_cmp_eq_u32 s10, 3
	s_cbranch_scc1 .Lattn_q6
